# m22 plus the same static priority raise for waves 0-3 in the dilated-attention task loop
# baseline (speedup 1.0000x reference)
; #define LAS __attribute__((address_space(3)))
; __device__ __forceinline__ void dil_task(const bf16_t* Z, bf16_t* OG, float* LSE, int S, int task, LAS unsigned char* wl, int lane_in) {
;     int lane = lane_in; asm volatile("" : "+v"(lane));
;     const int r32 = lane & 31, hi = lane >> 5;
;     const int bps = S >> 5, tps = 12 * bps;
;     const int seq = task / tps; const int rem = task - seq * tps; const int hd = rem / bps; const int blk = rem - hd * bps;
;     const int g = hd >> 2, sh = 2 * g, dl = 1 << sh; const int r = blk & (dl - 1), bi = blk >> sh;
;     const int i0 = bi * 32, nsub = S >> sh;
;     const size_t rowbase = (size_t)seq * S;
;     const int tq = r + ((i0 + r32) << sh);
; __global__ void __launch_bounds__(512, 2) fwd_kernel(Args args) {
;     ...
;                 LAS unsigned char* wl = lds + wave * 4096;
;                 for (int task = gw; task < CH * 12 / 32; task += NGW) dil_task(Zb, OGb, LSEb, P.S, task, wl, lane);
.LBB0_100:
	s_cmpk_gt_i32 s50, 0x17ff
	s_cbranch_scc1 .LBB0_105
	v_readfirstlane_b32 s100, v172
	s_nop 3
	s_cmp_ge_u32 s100, 0x100
	s_cbranch_scc1 .Ldil_prio
	s_setprio 1
.Ldil_prio:
	s_lshr_b32 s3, s12, 5
	s_mul_i32 s4, s3, 12
	v_cvt_f32_u32_e32 v0, s4
	v_readlane_b32 s0, v254, 27
	s_lshl_b32 s0, s0, 12
	s_add_i32 s2, s0, 0
	v_rcp_iflag_f32_e32 v0, v0
	s_sub_i32 s0, 0, s4
	s_mov_b32 s19, s50
	v_mul_f32_e32 v0, 0x4f7ffffe, v0
	v_cvt_u32_f32_e32 v0, v0
	s_nop 0
	v_readfirstlane_b32 s1, v0
	v_cvt_f32_u32_e32 v0, s3
	s_mul_i32 s0, s0, s1
	s_mul_hi_u32 s0, s1, s0
	s_add_i32 s13, s1, s0
	v_rcp_iflag_f32_e32 v0, v0
	s_sub_i32 s0, 0, s3
	v_mul_f32_e32 v0, 0x4f7ffffe, v0
	v_cvt_u32_f32_e32 v0, v0
	s_nop 0
	v_readfirstlane_b32 s1, v0
	s_mul_i32 s0, s0, s1
	s_mul_hi_u32 s0, s1, s0
	s_add_i32 s18, s1, s0
	s_branch .LBB0_103

; __global__ void __launch_bounds__(512, 2) fwd_kernel(Args args) {
;     ...
;                 for (int task = gw; task < CH * 12 / 32; task += NGW) dil_task(Zb, OGb, LSEb, P.S, task, wl, lane);
.LBB0_105:
	s_setprio 0
	s_mov_b64 s[34:35], 0
